# speedup vs baseline: 1.0054x; 1.0054x over previous
; __device__ __forceinline__ unsigned cvt_pk(float lo, float hi) { unsigned r; asm volatile("v_cvt_pk_bf16_f32 %0, %1, %2" : "=v"(r) : "v"(lo), "v"(hi)); return r; }
; __device__ __forceinline__ float sigm(float x) { return __builtin_amdgcn_rcpf(1.f + __expf(-x)); }
; #define GAS __attribute__((address_space(1)))
;     __device__ __forceinline__ void operator()(const f32x4 (&acc)[2][2][4][2], const UnitD& u, int wr, int wc, int fr, int fq) const {
;     ...
;         for (int bj = 0; bj < 2; ++bj) {
;             const bool gate = (u.pn * BM + bj * HALF + wc * 32) >= C_G;
; #pragma unroll
;             for (int ai = 0; ai < 2; ++ai)
; #pragma unroll
;                 for (int m = 0; m < 4; ++m) { GAS bf16_t* rowp = C + (size_t)(row0 + ai * HALF + m * 16) * NP;
;                     const f32x4 v0 = acc[ai][bj][m][0], v1 = acc[ai][bj][m][1];
;                     if (!gate) { u32x4 w; w.x = cvt_pk(v0[0], v0[1]); w.y = cvt_pk(v0[2], v0[3]); w.z = cvt_pk(v1[0], v1[1]); w.w = cvt_pk(v1[2], v1[3]);
;                         *(GAS u32x4*)(rowp + col0 + bj * HALF) = w; }
;                     else { unsigned b[8];
; #pragma unroll
;                         for (int j = 0; j < 4; ++j) { b[j] = (unsigned)(sigm(v0[j]) * 255.f + 0.5f); b[4 + j] = (unsigned)(sigm(v1[j]) * 255.f + 0.5f); }
;                         u32x2 w; w.x = b[0] | (b[1] << 8) | (b[2] << 16) | (b[3] << 24); w.y = b[4] | (b[5] << 8) | (b[6] << 16) | (b[7] << 24);
;                         *(GAS u32x2*)((GAS unsigned char*)(rowp + C_G) + (col0 + bj * HALF - C_G)) = w; } }
.Lg1_slow:
	s_cmpk_gt_u32 s31, 0x28
	s_cbranch_scc0 .Lg1_mixed
	v_readlane_b32 s8, v249, 2
	v_readlane_b32 s9, v249, 3
	s_lshl_b32 s11, s31, 8
	v_lshrrev_b32_e32 v253, 16, v250
	v_and_b32_e32 v254, 0xff, v250
	v_lshl_add_u32 v150, s30, 8, v253
	v_or_b32_e32 v144, s11, v254
	v_mul_lo_u32 v154, v150, s3
	v_add_u32_e32 v154, v154, v144
	v_add_u32_e32 v154, 0x2840, v154
	v_mov_b32_e32 v152, 0xbfb8aa3b
	v_mov_b32_e32 v153, 0xbfb8aa3b
	v_pk_mul_f32 v[126:127], v[126:127], v[152:153]
	v_pk_mul_f32 v[128:129], v[128:129], v[152:153]
	v_pk_mul_f32 v[122:123], v[122:123], v[152:153]
	v_pk_mul_f32 v[124:125], v[124:125], v[152:153]
	v_exp_f32_e32 v126, v126
	v_exp_f32_e32 v127, v127
	v_exp_f32_e32 v128, v128
	v_exp_f32_e32 v129, v129
	v_exp_f32_e32 v122, v122
	v_exp_f32_e32 v123, v123
	v_exp_f32_e32 v124, v124
	v_exp_f32_e32 v125, v125
	v_pk_add_f32 v[126:127], v[126:127], 1.0 op_sel_hi:[1,0]
	v_pk_add_f32 v[128:129], v[128:129], 1.0 op_sel_hi:[1,0]
	v_pk_add_f32 v[122:123], v[122:123], 1.0 op_sel_hi:[1,0]
	v_pk_add_f32 v[124:125], v[124:125], 1.0 op_sel_hi:[1,0]
	v_rcp_f32_e32 v126, v126
	v_rcp_f32_e32 v127, v127
	v_rcp_f32_e32 v128, v128
	v_rcp_f32_e32 v129, v129
	v_rcp_f32_e32 v122, v122
	v_rcp_f32_e32 v123, v123
	v_rcp_f32_e32 v124, v124
	v_rcp_f32_e32 v125, v125
	v_pk_fma_f32 v[126:127], v[126:127], s[86:87], 0.5 op_sel_hi:[1,0,0]
	v_pk_fma_f32 v[128:129], v[128:129], s[86:87], 0.5 op_sel_hi:[1,0,0]
	v_pk_fma_f32 v[122:123], v[122:123], s[86:87], 0.5 op_sel_hi:[1,0,0]
	v_pk_fma_f32 v[124:125], v[124:125], s[86:87], 0.5 op_sel_hi:[1,0,0]
	v_cvt_u32_f32_e32 v126, v126
	v_cvt_u32_f32_e32 v127, v127
	v_cvt_u32_f32_e32 v128, v128
	v_cvt_u32_f32_e32 v129, v129
	v_cvt_u32_f32_e32 v122, v122
	v_cvt_u32_f32_e32 v123, v123
	v_cvt_u32_f32_e32 v124, v124
	v_cvt_u32_f32_e32 v125, v125
	v_lshl_or_b32 v126, v127, 8, v126
	v_lshl_or_b32 v127, v123, 8, v122
	v_lshl_or_b32 v126, v128, 16, v126
	v_lshl_or_b32 v127, v124, 16, v127
	v_lshl_or_b32 v126, v129, 24, v126
	v_lshl_or_b32 v127, v125, 24, v127
	ds_write_b64 v251, v[126:127]
	ds_read_b64 v[126:127], v252
	v_pk_mul_f32 v[62:63], v[62:63], v[152:153]
	v_pk_mul_f32 v[64:65], v[64:65], v[152:153]
	v_pk_mul_f32 v[58:59], v[58:59], v[152:153]
	v_pk_mul_f32 v[60:61], v[60:61], v[152:153]
	v_exp_f32_e32 v62, v62
	v_exp_f32_e32 v63, v63
	v_exp_f32_e32 v64, v64
	v_exp_f32_e32 v65, v65
	v_exp_f32_e32 v58, v58
	v_exp_f32_e32 v59, v59
	v_exp_f32_e32 v60, v60
	v_exp_f32_e32 v61, v61
	v_pk_add_f32 v[62:63], v[62:63], 1.0 op_sel_hi:[1,0]
	v_pk_add_f32 v[64:65], v[64:65], 1.0 op_sel_hi:[1,0]
	v_pk_add_f32 v[58:59], v[58:59], 1.0 op_sel_hi:[1,0]
	v_pk_add_f32 v[60:61], v[60:61], 1.0 op_sel_hi:[1,0]
	v_rcp_f32_e32 v62, v62
	v_rcp_f32_e32 v63, v63
	v_rcp_f32_e32 v64, v64
	v_rcp_f32_e32 v65, v65
	v_rcp_f32_e32 v58, v58
	v_rcp_f32_e32 v59, v59
	v_rcp_f32_e32 v60, v60
	v_rcp_f32_e32 v61, v61
	v_pk_fma_f32 v[62:63], v[62:63], s[86:87], 0.5 op_sel_hi:[1,0,0]
	v_pk_fma_f32 v[64:65], v[64:65], s[86:87], 0.5 op_sel_hi:[1,0,0]
	v_pk_fma_f32 v[58:59], v[58:59], s[86:87], 0.5 op_sel_hi:[1,0,0]
	v_pk_fma_f32 v[60:61], v[60:61], s[86:87], 0.5 op_sel_hi:[1,0,0]
	v_cvt_u32_f32_e32 v62, v62
	v_cvt_u32_f32_e32 v63, v63
	v_cvt_u32_f32_e32 v64, v64
	v_cvt_u32_f32_e32 v65, v65
	v_cvt_u32_f32_e32 v58, v58
	v_cvt_u32_f32_e32 v59, v59
	v_cvt_u32_f32_e32 v60, v60
	v_cvt_u32_f32_e32 v61, v61
	v_lshl_or_b32 v62, v63, 8, v62
	v_lshl_or_b32 v63, v59, 8, v58
	v_lshl_or_b32 v62, v64, 16, v62
	v_lshl_or_b32 v63, v60, 16, v63
	v_lshl_or_b32 v62, v65, 24, v62
	v_lshl_or_b32 v63, v61, 24, v63
	ds_write_b64 v251, v[62:63]
	ds_read_b64 v[62:63], v252
	v_mov_b32_e32 v155, v154
	s_waitcnt lgkmcnt(2)
	global_store_dwordx2 v155, v[126:127], s[8:9]
	v_pk_mul_f32 v[118:119], v[118:119], v[152:153]
	v_pk_mul_f32 v[120:121], v[120:121], v[152:153]
	v_pk_mul_f32 v[114:115], v[114:115], v[152:153]
	v_pk_mul_f32 v[116:117], v[116:117], v[152:153]
	v_exp_f32_e32 v118, v118
	v_exp_f32_e32 v119, v119
	v_exp_f32_e32 v120, v120
	v_exp_f32_e32 v121, v121
	v_exp_f32_e32 v114, v114
	v_exp_f32_e32 v115, v115
	v_exp_f32_e32 v116, v116
	v_exp_f32_e32 v117, v117
	v_pk_add_f32 v[118:119], v[118:119], 1.0 op_sel_hi:[1,0]
	v_pk_add_f32 v[120:121], v[120:121], 1.0 op_sel_hi:[1,0]
	v_pk_add_f32 v[114:115], v[114:115], 1.0 op_sel_hi:[1,0]
	v_pk_add_f32 v[116:117], v[116:117], 1.0 op_sel_hi:[1,0]
	v_rcp_f32_e32 v118, v118
	v_rcp_f32_e32 v119, v119
	v_rcp_f32_e32 v120, v120
	v_rcp_f32_e32 v121, v121
	v_rcp_f32_e32 v114, v114
	v_rcp_f32_e32 v115, v115
	v_rcp_f32_e32 v116, v116
	v_rcp_f32_e32 v117, v117
	v_pk_fma_f32 v[118:119], v[118:119], s[86:87], 0.5 op_sel_hi:[1,0,0]
	v_pk_fma_f32 v[120:121], v[120:121], s[86:87], 0.5 op_sel_hi:[1,0,0]
	v_pk_fma_f32 v[114:115], v[114:115], s[86:87], 0.5 op_sel_hi:[1,0,0]
	v_pk_fma_f32 v[116:117], v[116:117], s[86:87], 0.5 op_sel_hi:[1,0,0]
	v_cvt_u32_f32_e32 v118, v118
	v_cvt_u32_f32_e32 v119, v119
	v_cvt_u32_f32_e32 v120, v120
	v_cvt_u32_f32_e32 v121, v121
	v_cvt_u32_f32_e32 v114, v114
	v_cvt_u32_f32_e32 v115, v115
	v_cvt_u32_f32_e32 v116, v116
	v_cvt_u32_f32_e32 v117, v117
	v_lshl_or_b32 v118, v119, 8, v118
	v_lshl_or_b32 v119, v115, 8, v114
	v_lshl_or_b32 v118, v120, 16, v118
	v_lshl_or_b32 v119, v116, 16, v119
	v_lshl_or_b32 v118, v121, 24, v118
	v_lshl_or_b32 v119, v117, 24, v119
	ds_write_b64 v251, v[118:119]
	ds_read_b64 v[118:119], v252
	s_waitcnt lgkmcnt(2)
; __device__ __forceinline__ unsigned cvt_pk(float lo, float hi) { unsigned r; asm volatile("v_cvt_pk_bf16_f32 %0, %1, %2" : "=v"(r) : "v"(lo), "v"(hi)); return r; }
; __device__ __forceinline__ float sigm(float x) { return __builtin_amdgcn_rcpf(1.f + __expf(-x)); }
; #define GAS __attribute__((address_space(1)))
;     __device__ __forceinline__ void operator()(const f32x4 (&acc)[2][2][4][2], const UnitD& u, int wr, int wc, int fr, int fq) const {
;     ...
;         for (int bj = 0; bj < 2; ++bj) {
;             const bool gate = (u.pn * BM + bj * HALF + wc * 32) >= C_G;
; #pragma unroll
;             for (int ai = 0; ai < 2; ++ai)
; #pragma unroll
;                 for (int m = 0; m < 4; ++m) { GAS bf16_t* rowp = C + (size_t)(row0 + ai * HALF + m * 16) * NP;
;                     const f32x4 v0 = acc[ai][bj][m][0], v1 = acc[ai][bj][m][1];
;                     if (!gate) { u32x4 w; w.x = cvt_pk(v0[0], v0[1]); w.y = cvt_pk(v0[2], v0[3]); w.z = cvt_pk(v1[0], v1[1]); w.w = cvt_pk(v1[2], v1[3]);
;                         *(GAS u32x4*)(rowp + col0 + bj * HALF) = w; }
;                     else { unsigned b[8];
; #pragma unroll
;                         for (int j = 0; j < 4; ++j) { b[j] = (unsigned)(sigm(v0[j]) * 255.f + 0.5f); b[4 + j] = (unsigned)(sigm(v1[j]) * 255.f + 0.5f); }
;                         u32x2 w; w.x = b[0] | (b[1] << 8) | (b[2] << 16) | (b[3] << 24); w.y = b[4] | (b[5] << 8) | (b[6] << 16) | (b[7] << 24);
;                         *(GAS u32x2*)((GAS unsigned char*)(rowp + C_G) + (col0 + bj * HALF - C_G)) = w; } }
	global_store_dwordx2 v155, v[62:63], s[8:9] offset:128
	v_pk_mul_f32 v[54:55], v[54:55], v[152:153]
	v_pk_mul_f32 v[56:57], v[56:57], v[152:153]
	v_pk_mul_f32 v[50:51], v[50:51], v[152:153]
	v_pk_mul_f32 v[52:53], v[52:53], v[152:153]
	v_exp_f32_e32 v54, v54
	v_exp_f32_e32 v55, v55
	v_exp_f32_e32 v56, v56
	v_exp_f32_e32 v57, v57
	v_exp_f32_e32 v50, v50
	v_exp_f32_e32 v51, v51
	v_exp_f32_e32 v52, v52
	v_exp_f32_e32 v53, v53
	v_pk_add_f32 v[54:55], v[54:55], 1.0 op_sel_hi:[1,0]
	v_pk_add_f32 v[56:57], v[56:57], 1.0 op_sel_hi:[1,0]
	v_pk_add_f32 v[50:51], v[50:51], 1.0 op_sel_hi:[1,0]
	v_pk_add_f32 v[52:53], v[52:53], 1.0 op_sel_hi:[1,0]
	v_rcp_f32_e32 v54, v54
	v_rcp_f32_e32 v55, v55
	v_rcp_f32_e32 v56, v56
	v_rcp_f32_e32 v57, v57
	v_rcp_f32_e32 v50, v50
	v_rcp_f32_e32 v51, v51
	v_rcp_f32_e32 v52, v52
	v_rcp_f32_e32 v53, v53
	v_pk_fma_f32 v[54:55], v[54:55], s[86:87], 0.5 op_sel_hi:[1,0,0]
	v_pk_fma_f32 v[56:57], v[56:57], s[86:87], 0.5 op_sel_hi:[1,0,0]
	v_pk_fma_f32 v[50:51], v[50:51], s[86:87], 0.5 op_sel_hi:[1,0,0]
	v_pk_fma_f32 v[52:53], v[52:53], s[86:87], 0.5 op_sel_hi:[1,0,0]
	v_cvt_u32_f32_e32 v54, v54
	v_cvt_u32_f32_e32 v55, v55
	v_cvt_u32_f32_e32 v56, v56
	v_cvt_u32_f32_e32 v57, v57
	v_cvt_u32_f32_e32 v50, v50
	v_cvt_u32_f32_e32 v51, v51
	v_cvt_u32_f32_e32 v52, v52
	v_cvt_u32_f32_e32 v53, v53
	v_lshl_or_b32 v54, v55, 8, v54
	v_lshl_or_b32 v55, v51, 8, v50
	v_lshl_or_b32 v54, v56, 16, v54
	v_lshl_or_b32 v55, v52, 16, v55
	v_lshl_or_b32 v54, v57, 24, v54
	v_lshl_or_b32 v55, v53, 24, v55
	ds_write_b64 v251, v[54:55]
	ds_read_b64 v[54:55], v252
	v_add_u32_e32 v155, 0x82000, v154
	s_waitcnt lgkmcnt(2)
	global_store_dwordx2 v155, v[118:119], s[8:9]
	v_pk_mul_f32 v[110:111], v[110:111], v[152:153]
	v_pk_mul_f32 v[112:113], v[112:113], v[152:153]
	v_pk_mul_f32 v[106:107], v[106:107], v[152:153]
	v_pk_mul_f32 v[108:109], v[108:109], v[152:153]
	v_exp_f32_e32 v110, v110
	v_exp_f32_e32 v111, v111
	v_exp_f32_e32 v112, v112
	v_exp_f32_e32 v113, v113
	v_exp_f32_e32 v106, v106
	v_exp_f32_e32 v107, v107
	v_exp_f32_e32 v108, v108
	v_exp_f32_e32 v109, v109
	v_pk_add_f32 v[110:111], v[110:111], 1.0 op_sel_hi:[1,0]
	v_pk_add_f32 v[112:113], v[112:113], 1.0 op_sel_hi:[1,0]
	v_pk_add_f32 v[106:107], v[106:107], 1.0 op_sel_hi:[1,0]
	v_pk_add_f32 v[108:109], v[108:109], 1.0 op_sel_hi:[1,0]
	v_rcp_f32_e32 v110, v110
	v_rcp_f32_e32 v111, v111
	v_rcp_f32_e32 v112, v112
	v_rcp_f32_e32 v113, v113
	v_rcp_f32_e32 v106, v106
	v_rcp_f32_e32 v107, v107
	v_rcp_f32_e32 v108, v108
	v_rcp_f32_e32 v109, v109
	v_pk_fma_f32 v[110:111], v[110:111], s[86:87], 0.5 op_sel_hi:[1,0,0]
	v_pk_fma_f32 v[112:113], v[112:113], s[86:87], 0.5 op_sel_hi:[1,0,0]
	v_pk_fma_f32 v[106:107], v[106:107], s[86:87], 0.5 op_sel_hi:[1,0,0]
	v_pk_fma_f32 v[108:109], v[108:109], s[86:87], 0.5 op_sel_hi:[1,0,0]
	v_cvt_u32_f32_e32 v110, v110
	v_cvt_u32_f32_e32 v111, v111
	v_cvt_u32_f32_e32 v112, v112
	v_cvt_u32_f32_e32 v113, v113
	v_cvt_u32_f32_e32 v106, v106
	v_cvt_u32_f32_e32 v107, v107
	v_cvt_u32_f32_e32 v108, v108
	v_cvt_u32_f32_e32 v109, v109
	v_lshl_or_b32 v110, v111, 8, v110
	v_lshl_or_b32 v111, v107, 8, v106
	v_lshl_or_b32 v110, v112, 16, v110
	v_lshl_or_b32 v111, v108, 16, v111
	v_lshl_or_b32 v110, v113, 24, v110
	v_lshl_or_b32 v111, v109, 24, v111
	ds_write_b64 v251, v[110:111]
	ds_read_b64 v[110:111], v252
	s_waitcnt lgkmcnt(2)
	global_store_dwordx2 v155, v[54:55], s[8:9] offset:128
	v_pk_mul_f32 v[46:47], v[46:47], v[152:153]
	v_pk_mul_f32 v[48:49], v[48:49], v[152:153]
	v_pk_mul_f32 v[42:43], v[42:43], v[152:153]
	v_pk_mul_f32 v[44:45], v[44:45], v[152:153]
	v_exp_f32_e32 v46, v46
	v_exp_f32_e32 v47, v47
	v_exp_f32_e32 v48, v48
	v_exp_f32_e32 v49, v49
	v_exp_f32_e32 v42, v42
	v_exp_f32_e32 v43, v43
	v_exp_f32_e32 v44, v44
	v_exp_f32_e32 v45, v45
	v_pk_add_f32 v[46:47], v[46:47], 1.0 op_sel_hi:[1,0]
	v_pk_add_f32 v[48:49], v[48:49], 1.0 op_sel_hi:[1,0]
	v_pk_add_f32 v[42:43], v[42:43], 1.0 op_sel_hi:[1,0]
	v_pk_add_f32 v[44:45], v[44:45], 1.0 op_sel_hi:[1,0]
	v_rcp_f32_e32 v46, v46
	v_rcp_f32_e32 v47, v47
	v_rcp_f32_e32 v48, v48
	v_rcp_f32_e32 v49, v49
	v_rcp_f32_e32 v42, v42
	v_rcp_f32_e32 v43, v43
	v_rcp_f32_e32 v44, v44
	v_rcp_f32_e32 v45, v45
	v_pk_fma_f32 v[46:47], v[46:47], s[86:87], 0.5 op_sel_hi:[1,0,0]
	v_pk_fma_f32 v[48:49], v[48:49], s[86:87], 0.5 op_sel_hi:[1,0,0]
	v_pk_fma_f32 v[42:43], v[42:43], s[86:87], 0.5 op_sel_hi:[1,0,0]
	v_pk_fma_f32 v[44:45], v[44:45], s[86:87], 0.5 op_sel_hi:[1,0,0]
	v_cvt_u32_f32_e32 v46, v46
	v_cvt_u32_f32_e32 v47, v47
	v_cvt_u32_f32_e32 v48, v48
	v_cvt_u32_f32_e32 v49, v49
	v_cvt_u32_f32_e32 v42, v42
	v_cvt_u32_f32_e32 v43, v43
	v_cvt_u32_f32_e32 v44, v44
	v_cvt_u32_f32_e32 v45, v45
	v_lshl_or_b32 v46, v47, 8, v46
	v_lshl_or_b32 v47, v43, 8, v42
	v_lshl_or_b32 v46, v48, 16, v46
	v_lshl_or_b32 v47, v44, 16, v47
	v_lshl_or_b32 v46, v49, 24, v46
	v_lshl_or_b32 v47, v45, 24, v47
	ds_write_b64 v251, v[46:47]
	ds_read_b64 v[46:47], v252
	v_add_u32_e32 v155, 0x104000, v154
	s_waitcnt lgkmcnt(2)
; __device__ __forceinline__ unsigned cvt_pk(float lo, float hi) { unsigned r; asm volatile("v_cvt_pk_bf16_f32 %0, %1, %2" : "=v"(r) : "v"(lo), "v"(hi)); return r; }
; __device__ __forceinline__ float sigm(float x) { return __builtin_amdgcn_rcpf(1.f + __expf(-x)); }
; #define GAS __attribute__((address_space(1)))
;     __device__ __forceinline__ void operator()(const f32x4 (&acc)[2][2][4][2], const UnitD& u, int wr, int wc, int fr, int fq) const {
;     ...
;         for (int bj = 0; bj < 2; ++bj) {
;             const bool gate = (u.pn * BM + bj * HALF + wc * 32) >= C_G;
; #pragma unroll
;             for (int ai = 0; ai < 2; ++ai)
; #pragma unroll
;                 for (int m = 0; m < 4; ++m) { GAS bf16_t* rowp = C + (size_t)(row0 + ai * HALF + m * 16) * NP;
;                     const f32x4 v0 = acc[ai][bj][m][0], v1 = acc[ai][bj][m][1];
;                     if (!gate) { u32x4 w; w.x = cvt_pk(v0[0], v0[1]); w.y = cvt_pk(v0[2], v0[3]); w.z = cvt_pk(v1[0], v1[1]); w.w = cvt_pk(v1[2], v1[3]);
;                         *(GAS u32x4*)(rowp + col0 + bj * HALF) = w; }
;                     else { unsigned b[8];
; #pragma unroll
;                         for (int j = 0; j < 4; ++j) { b[j] = (unsigned)(sigm(v0[j]) * 255.f + 0.5f); b[4 + j] = (unsigned)(sigm(v1[j]) * 255.f + 0.5f); }
;                         u32x2 w; w.x = b[0] | (b[1] << 8) | (b[2] << 16) | (b[3] << 24); w.y = b[4] | (b[5] << 8) | (b[6] << 16) | (b[7] << 24);
;                         *(GAS u32x2*)((GAS unsigned char*)(rowp + C_G) + (col0 + bj * HALF - C_G)) = w; } }
	global_store_dwordx2 v155, v[110:111], s[8:9]
	v_pk_mul_f32 v[102:103], v[102:103], v[152:153]
	v_pk_mul_f32 v[104:105], v[104:105], v[152:153]
	v_pk_mul_f32 v[98:99], v[98:99], v[152:153]
	v_pk_mul_f32 v[100:101], v[100:101], v[152:153]
	v_exp_f32_e32 v102, v102
	v_exp_f32_e32 v103, v103
	v_exp_f32_e32 v104, v104
	v_exp_f32_e32 v105, v105
	v_exp_f32_e32 v98, v98
	v_exp_f32_e32 v99, v99
	v_exp_f32_e32 v100, v100
	v_exp_f32_e32 v101, v101
	v_pk_add_f32 v[102:103], v[102:103], 1.0 op_sel_hi:[1,0]
	v_pk_add_f32 v[104:105], v[104:105], 1.0 op_sel_hi:[1,0]
	v_pk_add_f32 v[98:99], v[98:99], 1.0 op_sel_hi:[1,0]
	v_pk_add_f32 v[100:101], v[100:101], 1.0 op_sel_hi:[1,0]
	v_rcp_f32_e32 v102, v102
	v_rcp_f32_e32 v103, v103
	v_rcp_f32_e32 v104, v104
	v_rcp_f32_e32 v105, v105
	v_rcp_f32_e32 v98, v98
	v_rcp_f32_e32 v99, v99
	v_rcp_f32_e32 v100, v100
	v_rcp_f32_e32 v101, v101
	v_pk_fma_f32 v[102:103], v[102:103], s[86:87], 0.5 op_sel_hi:[1,0,0]
	v_pk_fma_f32 v[104:105], v[104:105], s[86:87], 0.5 op_sel_hi:[1,0,0]
	v_pk_fma_f32 v[98:99], v[98:99], s[86:87], 0.5 op_sel_hi:[1,0,0]
	v_pk_fma_f32 v[100:101], v[100:101], s[86:87], 0.5 op_sel_hi:[1,0,0]
	v_cvt_u32_f32_e32 v102, v102
	v_cvt_u32_f32_e32 v103, v103
	v_cvt_u32_f32_e32 v104, v104
	v_cvt_u32_f32_e32 v105, v105
	v_cvt_u32_f32_e32 v98, v98
	v_cvt_u32_f32_e32 v99, v99
	v_cvt_u32_f32_e32 v100, v100
	v_cvt_u32_f32_e32 v101, v101
	v_lshl_or_b32 v102, v103, 8, v102
	v_lshl_or_b32 v103, v99, 8, v98
	v_lshl_or_b32 v102, v104, 16, v102
	v_lshl_or_b32 v103, v100, 16, v103
	v_lshl_or_b32 v102, v105, 24, v102
	v_lshl_or_b32 v103, v101, 24, v103
	ds_write_b64 v251, v[102:103]
	ds_read_b64 v[102:103], v252
	s_waitcnt lgkmcnt(2)
	global_store_dwordx2 v155, v[46:47], s[8:9] offset:128
	v_pk_mul_f32 v[38:39], v[38:39], v[152:153]
	v_pk_mul_f32 v[40:41], v[40:41], v[152:153]
	v_pk_mul_f32 v[34:35], v[34:35], v[152:153]
	v_pk_mul_f32 v[36:37], v[36:37], v[152:153]
	v_exp_f32_e32 v38, v38
	v_exp_f32_e32 v39, v39
	v_exp_f32_e32 v40, v40
	v_exp_f32_e32 v41, v41
	v_exp_f32_e32 v34, v34
	v_exp_f32_e32 v35, v35
	v_exp_f32_e32 v36, v36
	v_exp_f32_e32 v37, v37
	v_pk_add_f32 v[38:39], v[38:39], 1.0 op_sel_hi:[1,0]
	v_pk_add_f32 v[40:41], v[40:41], 1.0 op_sel_hi:[1,0]
	v_pk_add_f32 v[34:35], v[34:35], 1.0 op_sel_hi:[1,0]
	v_pk_add_f32 v[36:37], v[36:37], 1.0 op_sel_hi:[1,0]
	v_rcp_f32_e32 v38, v38
	v_rcp_f32_e32 v39, v39
	v_rcp_f32_e32 v40, v40
	v_rcp_f32_e32 v41, v41
	v_rcp_f32_e32 v34, v34
	v_rcp_f32_e32 v35, v35
	v_rcp_f32_e32 v36, v36
	v_rcp_f32_e32 v37, v37
	v_pk_fma_f32 v[38:39], v[38:39], s[86:87], 0.5 op_sel_hi:[1,0,0]
	v_pk_fma_f32 v[40:41], v[40:41], s[86:87], 0.5 op_sel_hi:[1,0,0]
	v_pk_fma_f32 v[34:35], v[34:35], s[86:87], 0.5 op_sel_hi:[1,0,0]
	v_pk_fma_f32 v[36:37], v[36:37], s[86:87], 0.5 op_sel_hi:[1,0,0]
	v_cvt_u32_f32_e32 v38, v38
	v_cvt_u32_f32_e32 v39, v39
	v_cvt_u32_f32_e32 v40, v40
	v_cvt_u32_f32_e32 v41, v41
	v_cvt_u32_f32_e32 v34, v34
	v_cvt_u32_f32_e32 v35, v35
	v_cvt_u32_f32_e32 v36, v36
	v_cvt_u32_f32_e32 v37, v37
	v_lshl_or_b32 v38, v39, 8, v38
	v_lshl_or_b32 v39, v35, 8, v34
	v_lshl_or_b32 v38, v40, 16, v38
	v_lshl_or_b32 v39, v36, 16, v39
	v_lshl_or_b32 v38, v41, 24, v38
	v_lshl_or_b32 v39, v37, 24, v39
	ds_write_b64 v251, v[38:39]
	ds_read_b64 v[38:39], v252
	v_add_u32_e32 v155, 0x186000, v154
	s_waitcnt lgkmcnt(2)
	global_store_dwordx2 v155, v[102:103], s[8:9]
	v_pk_mul_f32 v[94:95], v[94:95], v[152:153]
	v_pk_mul_f32 v[96:97], v[96:97], v[152:153]
	v_pk_mul_f32 v[90:91], v[90:91], v[152:153]
	v_pk_mul_f32 v[92:93], v[92:93], v[152:153]
	v_exp_f32_e32 v94, v94
	v_exp_f32_e32 v95, v95
	v_exp_f32_e32 v96, v96
	v_exp_f32_e32 v97, v97
	v_exp_f32_e32 v90, v90
	v_exp_f32_e32 v91, v91
	v_exp_f32_e32 v92, v92
	v_exp_f32_e32 v93, v93
	v_pk_add_f32 v[94:95], v[94:95], 1.0 op_sel_hi:[1,0]
	v_pk_add_f32 v[96:97], v[96:97], 1.0 op_sel_hi:[1,0]
	v_pk_add_f32 v[90:91], v[90:91], 1.0 op_sel_hi:[1,0]
	v_pk_add_f32 v[92:93], v[92:93], 1.0 op_sel_hi:[1,0]
	v_rcp_f32_e32 v94, v94
	v_rcp_f32_e32 v95, v95
	v_rcp_f32_e32 v96, v96
	v_rcp_f32_e32 v97, v97
	v_rcp_f32_e32 v90, v90
	v_rcp_f32_e32 v91, v91
	v_rcp_f32_e32 v92, v92
	v_rcp_f32_e32 v93, v93
	v_pk_fma_f32 v[94:95], v[94:95], s[86:87], 0.5 op_sel_hi:[1,0,0]
	v_pk_fma_f32 v[96:97], v[96:97], s[86:87], 0.5 op_sel_hi:[1,0,0]
	v_pk_fma_f32 v[90:91], v[90:91], s[86:87], 0.5 op_sel_hi:[1,0,0]
	v_pk_fma_f32 v[92:93], v[92:93], s[86:87], 0.5 op_sel_hi:[1,0,0]
	v_cvt_u32_f32_e32 v94, v94
	v_cvt_u32_f32_e32 v95, v95
	v_cvt_u32_f32_e32 v96, v96
	v_cvt_u32_f32_e32 v97, v97
	v_cvt_u32_f32_e32 v90, v90
	v_cvt_u32_f32_e32 v91, v91
	v_cvt_u32_f32_e32 v92, v92
	v_cvt_u32_f32_e32 v93, v93
	v_lshl_or_b32 v94, v95, 8, v94
	v_lshl_or_b32 v95, v91, 8, v90
	v_lshl_or_b32 v94, v96, 16, v94
	v_lshl_or_b32 v95, v92, 16, v95
	v_lshl_or_b32 v94, v97, 24, v94
	v_lshl_or_b32 v95, v93, 24, v95
	ds_write_b64 v251, v[94:95]
	ds_read_b64 v[94:95], v252
	s_waitcnt lgkmcnt(2)
; __device__ __forceinline__ unsigned cvt_pk(float lo, float hi) { unsigned r; asm volatile("v_cvt_pk_bf16_f32 %0, %1, %2" : "=v"(r) : "v"(lo), "v"(hi)); return r; }
; __device__ __forceinline__ float sigm(float x) { return __builtin_amdgcn_rcpf(1.f + __expf(-x)); }
; #define GAS __attribute__((address_space(1)))
;     __device__ __forceinline__ void operator()(const f32x4 (&acc)[2][2][4][2], const UnitD& u, int wr, int wc, int fr, int fq) const {
;     ...
;         for (int bj = 0; bj < 2; ++bj) {
;             const bool gate = (u.pn * BM + bj * HALF + wc * 32) >= C_G;
; #pragma unroll
;             for (int ai = 0; ai < 2; ++ai)
; #pragma unroll
;                 for (int m = 0; m < 4; ++m) { GAS bf16_t* rowp = C + (size_t)(row0 + ai * HALF + m * 16) * NP;
;                     const f32x4 v0 = acc[ai][bj][m][0], v1 = acc[ai][bj][m][1];
;                     if (!gate) { u32x4 w; w.x = cvt_pk(v0[0], v0[1]); w.y = cvt_pk(v0[2], v0[3]); w.z = cvt_pk(v1[0], v1[1]); w.w = cvt_pk(v1[2], v1[3]);
;                         *(GAS u32x4*)(rowp + col0 + bj * HALF) = w; }
;                     else { unsigned b[8];
; #pragma unroll
;                         for (int j = 0; j < 4; ++j) { b[j] = (unsigned)(sigm(v0[j]) * 255.f + 0.5f); b[4 + j] = (unsigned)(sigm(v1[j]) * 255.f + 0.5f); }
;                         u32x2 w; w.x = b[0] | (b[1] << 8) | (b[2] << 16) | (b[3] << 24); w.y = b[4] | (b[5] << 8) | (b[6] << 16) | (b[7] << 24);
;                         *(GAS u32x2*)((GAS unsigned char*)(rowp + C_G) + (col0 + bj * HALF - C_G)) = w; } }
	global_store_dwordx2 v155, v[38:39], s[8:9] offset:128
	v_pk_mul_f32 v[30:31], v[30:31], v[152:153]
	v_pk_mul_f32 v[32:33], v[32:33], v[152:153]
	v_pk_mul_f32 v[26:27], v[26:27], v[152:153]
	v_pk_mul_f32 v[28:29], v[28:29], v[152:153]
	v_exp_f32_e32 v30, v30
	v_exp_f32_e32 v31, v31
	v_exp_f32_e32 v32, v32
	v_exp_f32_e32 v33, v33
	v_exp_f32_e32 v26, v26
	v_exp_f32_e32 v27, v27
	v_exp_f32_e32 v28, v28
	v_exp_f32_e32 v29, v29
	v_pk_add_f32 v[30:31], v[30:31], 1.0 op_sel_hi:[1,0]
	v_pk_add_f32 v[32:33], v[32:33], 1.0 op_sel_hi:[1,0]
	v_pk_add_f32 v[26:27], v[26:27], 1.0 op_sel_hi:[1,0]
	v_pk_add_f32 v[28:29], v[28:29], 1.0 op_sel_hi:[1,0]
	v_rcp_f32_e32 v30, v30
	v_rcp_f32_e32 v31, v31
	v_rcp_f32_e32 v32, v32
	v_rcp_f32_e32 v33, v33
	v_rcp_f32_e32 v26, v26
	v_rcp_f32_e32 v27, v27
	v_rcp_f32_e32 v28, v28
	v_rcp_f32_e32 v29, v29
	v_pk_fma_f32 v[30:31], v[30:31], s[86:87], 0.5 op_sel_hi:[1,0,0]
	v_pk_fma_f32 v[32:33], v[32:33], s[86:87], 0.5 op_sel_hi:[1,0,0]
	v_pk_fma_f32 v[26:27], v[26:27], s[86:87], 0.5 op_sel_hi:[1,0,0]
	v_pk_fma_f32 v[28:29], v[28:29], s[86:87], 0.5 op_sel_hi:[1,0,0]
	v_cvt_u32_f32_e32 v30, v30
	v_cvt_u32_f32_e32 v31, v31
	v_cvt_u32_f32_e32 v32, v32
	v_cvt_u32_f32_e32 v33, v33
	v_cvt_u32_f32_e32 v26, v26
	v_cvt_u32_f32_e32 v27, v27
	v_cvt_u32_f32_e32 v28, v28
	v_cvt_u32_f32_e32 v29, v29
	v_lshl_or_b32 v30, v31, 8, v30
	v_lshl_or_b32 v31, v27, 8, v26
	v_lshl_or_b32 v30, v32, 16, v30
	v_lshl_or_b32 v31, v28, 16, v31
	v_lshl_or_b32 v30, v33, 24, v30
	v_lshl_or_b32 v31, v29, 24, v31
	ds_write_b64 v251, v[30:31]
	ds_read_b64 v[30:31], v252
	v_add_u32_e32 v155, 0x410000, v154
	s_waitcnt lgkmcnt(2)
	global_store_dwordx2 v155, v[94:95], s[8:9]
	v_pk_mul_f32 v[86:87], v[86:87], v[152:153]
	v_pk_mul_f32 v[88:89], v[88:89], v[152:153]
	v_pk_mul_f32 v[82:83], v[82:83], v[152:153]
	v_pk_mul_f32 v[84:85], v[84:85], v[152:153]
	v_exp_f32_e32 v86, v86
	v_exp_f32_e32 v87, v87
	v_exp_f32_e32 v88, v88
	v_exp_f32_e32 v89, v89
	v_exp_f32_e32 v82, v82
	v_exp_f32_e32 v83, v83
	v_exp_f32_e32 v84, v84
	v_exp_f32_e32 v85, v85
	v_pk_add_f32 v[86:87], v[86:87], 1.0 op_sel_hi:[1,0]
	v_pk_add_f32 v[88:89], v[88:89], 1.0 op_sel_hi:[1,0]
	v_pk_add_f32 v[82:83], v[82:83], 1.0 op_sel_hi:[1,0]
	v_pk_add_f32 v[84:85], v[84:85], 1.0 op_sel_hi:[1,0]
	v_rcp_f32_e32 v86, v86
	v_rcp_f32_e32 v87, v87
	v_rcp_f32_e32 v88, v88
	v_rcp_f32_e32 v89, v89
	v_rcp_f32_e32 v82, v82
	v_rcp_f32_e32 v83, v83
	v_rcp_f32_e32 v84, v84
	v_rcp_f32_e32 v85, v85
	v_pk_fma_f32 v[86:87], v[86:87], s[86:87], 0.5 op_sel_hi:[1,0,0]
	v_pk_fma_f32 v[88:89], v[88:89], s[86:87], 0.5 op_sel_hi:[1,0,0]
	v_pk_fma_f32 v[82:83], v[82:83], s[86:87], 0.5 op_sel_hi:[1,0,0]
	v_pk_fma_f32 v[84:85], v[84:85], s[86:87], 0.5 op_sel_hi:[1,0,0]
	v_cvt_u32_f32_e32 v86, v86
	v_cvt_u32_f32_e32 v87, v87
	v_cvt_u32_f32_e32 v88, v88
	v_cvt_u32_f32_e32 v89, v89
	v_cvt_u32_f32_e32 v82, v82
	v_cvt_u32_f32_e32 v83, v83
	v_cvt_u32_f32_e32 v84, v84
	v_cvt_u32_f32_e32 v85, v85
	v_lshl_or_b32 v86, v87, 8, v86
	v_lshl_or_b32 v87, v83, 8, v82
	v_lshl_or_b32 v86, v88, 16, v86
	v_lshl_or_b32 v87, v84, 16, v87
	v_lshl_or_b32 v86, v89, 24, v86
	v_lshl_or_b32 v87, v85, 24, v87
	ds_write_b64 v251, v[86:87]
	ds_read_b64 v[86:87], v252
	s_waitcnt lgkmcnt(2)
	global_store_dwordx2 v155, v[30:31], s[8:9] offset:128
	v_pk_mul_f32 v[22:23], v[22:23], v[152:153]
	v_pk_mul_f32 v[24:25], v[24:25], v[152:153]
	v_pk_mul_f32 v[18:19], v[18:19], v[152:153]
	v_pk_mul_f32 v[20:21], v[20:21], v[152:153]
	v_exp_f32_e32 v22, v22
	v_exp_f32_e32 v23, v23
	v_exp_f32_e32 v24, v24
	v_exp_f32_e32 v25, v25
	v_exp_f32_e32 v18, v18
	v_exp_f32_e32 v19, v19
	v_exp_f32_e32 v20, v20
	v_exp_f32_e32 v21, v21
	v_pk_add_f32 v[22:23], v[22:23], 1.0 op_sel_hi:[1,0]
	v_pk_add_f32 v[24:25], v[24:25], 1.0 op_sel_hi:[1,0]
	v_pk_add_f32 v[18:19], v[18:19], 1.0 op_sel_hi:[1,0]
	v_pk_add_f32 v[20:21], v[20:21], 1.0 op_sel_hi:[1,0]
	v_rcp_f32_e32 v22, v22
	v_rcp_f32_e32 v23, v23
	v_rcp_f32_e32 v24, v24
	v_rcp_f32_e32 v25, v25
	v_rcp_f32_e32 v18, v18
	v_rcp_f32_e32 v19, v19
	v_rcp_f32_e32 v20, v20
	v_rcp_f32_e32 v21, v21
	v_pk_fma_f32 v[22:23], v[22:23], s[86:87], 0.5 op_sel_hi:[1,0,0]
	v_pk_fma_f32 v[24:25], v[24:25], s[86:87], 0.5 op_sel_hi:[1,0,0]
	v_pk_fma_f32 v[18:19], v[18:19], s[86:87], 0.5 op_sel_hi:[1,0,0]
	v_pk_fma_f32 v[20:21], v[20:21], s[86:87], 0.5 op_sel_hi:[1,0,0]
	v_cvt_u32_f32_e32 v22, v22
	v_cvt_u32_f32_e32 v23, v23
	v_cvt_u32_f32_e32 v24, v24
	v_cvt_u32_f32_e32 v25, v25
	v_cvt_u32_f32_e32 v18, v18
	v_cvt_u32_f32_e32 v19, v19
	v_cvt_u32_f32_e32 v20, v20
	v_cvt_u32_f32_e32 v21, v21
	v_lshl_or_b32 v22, v23, 8, v22
	v_lshl_or_b32 v23, v19, 8, v18
	v_lshl_or_b32 v22, v24, 16, v22
	v_lshl_or_b32 v23, v20, 16, v23
	v_lshl_or_b32 v22, v25, 24, v22
	v_lshl_or_b32 v23, v21, 24, v23
	ds_write_b64 v251, v[22:23]
	ds_read_b64 v[22:23], v252
	v_add_u32_e32 v155, 0x492000, v154
	s_waitcnt lgkmcnt(2)
; __device__ __forceinline__ unsigned cvt_pk(float lo, float hi) { unsigned r; asm volatile("v_cvt_pk_bf16_f32 %0, %1, %2" : "=v"(r) : "v"(lo), "v"(hi)); return r; }
; __device__ __forceinline__ float sigm(float x) { return __builtin_amdgcn_rcpf(1.f + __expf(-x)); }
; #define GAS __attribute__((address_space(1)))
;     __device__ __forceinline__ void operator()(const f32x4 (&acc)[2][2][4][2], const UnitD& u, int wr, int wc, int fr, int fq) const {
;     ...
;         for (int bj = 0; bj < 2; ++bj) {
;             const bool gate = (u.pn * BM + bj * HALF + wc * 32) >= C_G;
; #pragma unroll
;             for (int ai = 0; ai < 2; ++ai)
; #pragma unroll
;                 for (int m = 0; m < 4; ++m) { GAS bf16_t* rowp = C + (size_t)(row0 + ai * HALF + m * 16) * NP;
;                     const f32x4 v0 = acc[ai][bj][m][0], v1 = acc[ai][bj][m][1];
;                     if (!gate) { u32x4 w; w.x = cvt_pk(v0[0], v0[1]); w.y = cvt_pk(v0[2], v0[3]); w.z = cvt_pk(v1[0], v1[1]); w.w = cvt_pk(v1[2], v1[3]);
;                         *(GAS u32x4*)(rowp + col0 + bj * HALF) = w; }
;                     else { unsigned b[8];
; #pragma unroll
;                         for (int j = 0; j < 4; ++j) { b[j] = (unsigned)(sigm(v0[j]) * 255.f + 0.5f); b[4 + j] = (unsigned)(sigm(v1[j]) * 255.f + 0.5f); }
;                         u32x2 w; w.x = b[0] | (b[1] << 8) | (b[2] << 16) | (b[3] << 24); w.y = b[4] | (b[5] << 8) | (b[6] << 16) | (b[7] << 24);
;                         *(GAS u32x2*)((GAS unsigned char*)(rowp + C_G) + (col0 + bj * HALF - C_G)) = w; } }
	global_store_dwordx2 v155, v[86:87], s[8:9]
	v_pk_mul_f32 v[78:79], v[78:79], v[152:153]
	v_pk_mul_f32 v[80:81], v[80:81], v[152:153]
	v_pk_mul_f32 v[74:75], v[74:75], v[152:153]
	v_pk_mul_f32 v[76:77], v[76:77], v[152:153]
	v_exp_f32_e32 v78, v78
	v_exp_f32_e32 v79, v79
	v_exp_f32_e32 v80, v80
	v_exp_f32_e32 v81, v81
	v_exp_f32_e32 v74, v74
	v_exp_f32_e32 v75, v75
	v_exp_f32_e32 v76, v76
	v_exp_f32_e32 v77, v77
	v_pk_add_f32 v[78:79], v[78:79], 1.0 op_sel_hi:[1,0]
	v_pk_add_f32 v[80:81], v[80:81], 1.0 op_sel_hi:[1,0]
	v_pk_add_f32 v[74:75], v[74:75], 1.0 op_sel_hi:[1,0]
	v_pk_add_f32 v[76:77], v[76:77], 1.0 op_sel_hi:[1,0]
	v_rcp_f32_e32 v78, v78
	v_rcp_f32_e32 v79, v79
	v_rcp_f32_e32 v80, v80
	v_rcp_f32_e32 v81, v81
	v_rcp_f32_e32 v74, v74
	v_rcp_f32_e32 v75, v75
	v_rcp_f32_e32 v76, v76
	v_rcp_f32_e32 v77, v77
	v_pk_fma_f32 v[78:79], v[78:79], s[86:87], 0.5 op_sel_hi:[1,0,0]
	v_pk_fma_f32 v[80:81], v[80:81], s[86:87], 0.5 op_sel_hi:[1,0,0]
	v_pk_fma_f32 v[74:75], v[74:75], s[86:87], 0.5 op_sel_hi:[1,0,0]
	v_pk_fma_f32 v[76:77], v[76:77], s[86:87], 0.5 op_sel_hi:[1,0,0]
	v_cvt_u32_f32_e32 v78, v78
	v_cvt_u32_f32_e32 v79, v79
	v_cvt_u32_f32_e32 v80, v80
	v_cvt_u32_f32_e32 v81, v81
	v_cvt_u32_f32_e32 v74, v74
	v_cvt_u32_f32_e32 v75, v75
	v_cvt_u32_f32_e32 v76, v76
	v_cvt_u32_f32_e32 v77, v77
	v_lshl_or_b32 v78, v79, 8, v78
	v_lshl_or_b32 v79, v75, 8, v74
	v_lshl_or_b32 v78, v80, 16, v78
	v_lshl_or_b32 v79, v76, 16, v79
	v_lshl_or_b32 v78, v81, 24, v78
	v_lshl_or_b32 v79, v77, 24, v79
	ds_write_b64 v251, v[78:79]
	ds_read_b64 v[78:79], v252
	s_waitcnt lgkmcnt(2)
	global_store_dwordx2 v155, v[22:23], s[8:9] offset:128
	v_pk_mul_f32 v[14:15], v[14:15], v[152:153]
	v_pk_mul_f32 v[16:17], v[16:17], v[152:153]
	v_pk_mul_f32 v[10:11], v[10:11], v[152:153]
	v_pk_mul_f32 v[12:13], v[12:13], v[152:153]
	v_exp_f32_e32 v14, v14
	v_exp_f32_e32 v15, v15
	v_exp_f32_e32 v16, v16
	v_exp_f32_e32 v17, v17
	v_exp_f32_e32 v10, v10
	v_exp_f32_e32 v11, v11
	v_exp_f32_e32 v12, v12
	v_exp_f32_e32 v13, v13
	v_pk_add_f32 v[14:15], v[14:15], 1.0 op_sel_hi:[1,0]
	v_pk_add_f32 v[16:17], v[16:17], 1.0 op_sel_hi:[1,0]
	v_pk_add_f32 v[10:11], v[10:11], 1.0 op_sel_hi:[1,0]
	v_pk_add_f32 v[12:13], v[12:13], 1.0 op_sel_hi:[1,0]
	v_rcp_f32_e32 v14, v14
	v_rcp_f32_e32 v15, v15
	v_rcp_f32_e32 v16, v16
	v_rcp_f32_e32 v17, v17
	v_rcp_f32_e32 v10, v10
	v_rcp_f32_e32 v11, v11
	v_rcp_f32_e32 v12, v12
	v_rcp_f32_e32 v13, v13
	v_pk_fma_f32 v[14:15], v[14:15], s[86:87], 0.5 op_sel_hi:[1,0,0]
	v_pk_fma_f32 v[16:17], v[16:17], s[86:87], 0.5 op_sel_hi:[1,0,0]
	v_pk_fma_f32 v[10:11], v[10:11], s[86:87], 0.5 op_sel_hi:[1,0,0]
	v_pk_fma_f32 v[12:13], v[12:13], s[86:87], 0.5 op_sel_hi:[1,0,0]
	v_cvt_u32_f32_e32 v14, v14
	v_cvt_u32_f32_e32 v15, v15
	v_cvt_u32_f32_e32 v16, v16
	v_cvt_u32_f32_e32 v17, v17
	v_cvt_u32_f32_e32 v10, v10
	v_cvt_u32_f32_e32 v11, v11
	v_cvt_u32_f32_e32 v12, v12
	v_cvt_u32_f32_e32 v13, v13
	v_lshl_or_b32 v14, v15, 8, v14
	v_lshl_or_b32 v15, v11, 8, v10
	v_lshl_or_b32 v14, v16, 16, v14
	v_lshl_or_b32 v15, v12, 16, v15
	v_lshl_or_b32 v14, v17, 24, v14
	v_lshl_or_b32 v15, v13, 24, v15
	ds_write_b64 v251, v[14:15]
	ds_read_b64 v[14:15], v252
	v_add_u32_e32 v155, 0x514000, v154
	s_waitcnt lgkmcnt(2)
	global_store_dwordx2 v155, v[78:79], s[8:9]
	v_pk_mul_f32 v[70:71], v[70:71], v[152:153]
	v_pk_mul_f32 v[72:73], v[72:73], v[152:153]
	v_pk_mul_f32 v[66:67], v[66:67], v[152:153]
	v_pk_mul_f32 v[68:69], v[68:69], v[152:153]
	v_exp_f32_e32 v70, v70
	v_exp_f32_e32 v71, v71
	v_exp_f32_e32 v72, v72
	v_exp_f32_e32 v73, v73
	v_exp_f32_e32 v66, v66
	v_exp_f32_e32 v67, v67
	v_exp_f32_e32 v68, v68
	v_exp_f32_e32 v69, v69
	v_pk_add_f32 v[70:71], v[70:71], 1.0 op_sel_hi:[1,0]
	v_pk_add_f32 v[72:73], v[72:73], 1.0 op_sel_hi:[1,0]
	v_pk_add_f32 v[66:67], v[66:67], 1.0 op_sel_hi:[1,0]
	v_pk_add_f32 v[68:69], v[68:69], 1.0 op_sel_hi:[1,0]
	v_rcp_f32_e32 v70, v70
	v_rcp_f32_e32 v71, v71
	v_rcp_f32_e32 v72, v72
	v_rcp_f32_e32 v73, v73
	v_rcp_f32_e32 v66, v66
	v_rcp_f32_e32 v67, v67
	v_rcp_f32_e32 v68, v68
	v_rcp_f32_e32 v69, v69
	v_pk_fma_f32 v[70:71], v[70:71], s[86:87], 0.5 op_sel_hi:[1,0,0]
	v_pk_fma_f32 v[72:73], v[72:73], s[86:87], 0.5 op_sel_hi:[1,0,0]
	v_pk_fma_f32 v[66:67], v[66:67], s[86:87], 0.5 op_sel_hi:[1,0,0]
	v_pk_fma_f32 v[68:69], v[68:69], s[86:87], 0.5 op_sel_hi:[1,0,0]
	v_cvt_u32_f32_e32 v70, v70
	v_cvt_u32_f32_e32 v71, v71
	v_cvt_u32_f32_e32 v72, v72
	v_cvt_u32_f32_e32 v73, v73
	v_cvt_u32_f32_e32 v66, v66
	v_cvt_u32_f32_e32 v67, v67
	v_cvt_u32_f32_e32 v68, v68
	v_cvt_u32_f32_e32 v69, v69
	v_lshl_or_b32 v70, v71, 8, v70
	v_lshl_or_b32 v71, v67, 8, v66
	v_lshl_or_b32 v70, v72, 16, v70
	v_lshl_or_b32 v71, v68, 16, v71
	v_lshl_or_b32 v70, v73, 24, v70
	v_lshl_or_b32 v71, v69, 24, v71
	ds_write_b64 v251, v[70:71]
	ds_read_b64 v[70:71], v252
	s_waitcnt lgkmcnt(2)
	global_store_dwordx2 v155, v[14:15], s[8:9] offset:128
	v_pk_mul_f32 v[6:7], v[6:7], v[152:153]
	v_pk_mul_f32 v[8:9], v[8:9], v[152:153]
	v_pk_mul_f32 v[2:3], v[2:3], v[152:153]
	v_pk_mul_f32 v[4:5], v[4:5], v[152:153]
	v_exp_f32_e32 v6, v6
	v_exp_f32_e32 v7, v7
	v_exp_f32_e32 v8, v8
	v_exp_f32_e32 v9, v9
	v_exp_f32_e32 v2, v2
	v_exp_f32_e32 v3, v3
	v_exp_f32_e32 v4, v4
	v_exp_f32_e32 v5, v5
	v_pk_add_f32 v[6:7], v[6:7], 1.0 op_sel_hi:[1,0]
	v_pk_add_f32 v[8:9], v[8:9], 1.0 op_sel_hi:[1,0]
	v_pk_add_f32 v[2:3], v[2:3], 1.0 op_sel_hi:[1,0]
	v_pk_add_f32 v[4:5], v[4:5], 1.0 op_sel_hi:[1,0]
	v_rcp_f32_e32 v6, v6
	v_rcp_f32_e32 v7, v7
	v_rcp_f32_e32 v8, v8
	v_rcp_f32_e32 v9, v9
	v_rcp_f32_e32 v2, v2
	v_rcp_f32_e32 v3, v3
	v_rcp_f32_e32 v4, v4
	v_rcp_f32_e32 v5, v5
	v_pk_fma_f32 v[6:7], v[6:7], s[86:87], 0.5 op_sel_hi:[1,0,0]
	v_pk_fma_f32 v[8:9], v[8:9], s[86:87], 0.5 op_sel_hi:[1,0,0]
	v_pk_fma_f32 v[2:3], v[2:3], s[86:87], 0.5 op_sel_hi:[1,0,0]
	v_pk_fma_f32 v[4:5], v[4:5], s[86:87], 0.5 op_sel_hi:[1,0,0]
	v_cvt_u32_f32_e32 v6, v6
	v_cvt_u32_f32_e32 v7, v7
	v_cvt_u32_f32_e32 v8, v8
	v_cvt_u32_f32_e32 v9, v9
	v_cvt_u32_f32_e32 v2, v2
	v_cvt_u32_f32_e32 v3, v3
	v_cvt_u32_f32_e32 v4, v4
	v_cvt_u32_f32_e32 v5, v5
	v_lshl_or_b32 v6, v7, 8, v6
	v_lshl_or_b32 v7, v3, 8, v2
	v_lshl_or_b32 v6, v8, 16, v6
	v_lshl_or_b32 v7, v4, 16, v7
	v_lshl_or_b32 v6, v9, 24, v6
	v_lshl_or_b32 v7, v5, 24, v7
	ds_write_b64 v251, v[6:7]
	ds_read_b64 v[6:7], v252
	v_add_u32_e32 v155, 0x596000, v154
	s_waitcnt lgkmcnt(2)
	global_store_dwordx2 v155, v[70:71], s[8:9]
	s_waitcnt lgkmcnt(0)
	global_store_dwordx2 v155, v[6:7], s[8:9] offset:128
	s_branch .LBB0_241
